# one static s_setprio 1 for waves 4-7 across the attention units (reset before conv), no per-segment flips
# baseline (speedup 1.0000x reference)
.LBB0_1292:
	s_cmp_ge_u32 s33, 4
	s_cbranch_scc0 .Lprio_att_done
	s_setprio 1

.LBB0_1398:
	s_setprio 0
	s_mov_b32 s2, 9
	s_waitcnt lgkmcnt(0)
	s_barrier
	s_ashr_i32 s3, s2, 31
	s_lshl_b64 s[2:3], s[2:3], 3
	s_add_u32 s2, s0, s2
	s_addc_u32 s3, s1, s3
	s_load_dwordx2 s[2:3], s[2:3], 0x0
	v_readlane_b32 s6, v255, 18
	s_mul_i32 s5, s6, 0xf800
	s_mov_b32 s4, s33
	v_mov_b32_e32 v2, 0
	s_waitcnt lgkmcnt(0)
	s_add_u32 s22, s2, s5
	s_mov_b32 s2, -1
	s_addc_u32 s23, s3, 0
	v_mbcnt_lo_u32_b32 v0, s2, 0
	v_mbcnt_hi_u32_b32 v0, s2, v0
	v_lshl_or_b32 v34, s4, 6, v0
	s_movk_i32 s2, 0xf80
	v_mov_b32_e32 v6, 0
	v_cmp_gt_i32_e64 s[2:3], s2, v34
	v_ashrrev_i32_e32 v35, 31, v34
	v_mov_b32_e32 v7, 0
	v_mov_b32_e32 v8, 0
	v_mov_b32_e32 v9, 0
	v_readlane_b32 s7, v255, 19
	s_and_saveexec_b64 s[4:5], s[2:3]
	s_cbranch_execz .LBB0_1400
	v_lshl_add_u64 v[4:5], v[34:35], 4, s[22:23]
	global_load_dwordx4 v[6:9], v[4:5], off sc1
